# kernel code lines loaded into L2 at entry by workgroups 0-7 (one per XCD): later phases' first instruction fetches hit L2
# baseline (speedup 1.0000x reference)
_Z10hybrid_fwd3Prmii:
	s_mov_b32 s90, s2
	s_load_dwordx2 s[96:97], s[0:1], 0x110
	s_load_dwordx4 s[12:15], s[0:1], 0x100
	s_load_dword s2, s[0:1], 0x128
	s_load_dwordx2 s[92:93], s[0:1], 0x120
	s_add_u32 s4, s0, 0x120
	v_and_b32_e32 v153, 0x3ff, v0
	s_cmp_lt_u32 s90, 8
	s_cbranch_scc0 .Lpf_done
	s_getpc_b64 s[98:99]
	v_lshlrev_b32_e32 v249, 6, v153
	global_load_dword v250, v249, s[98:99]
	s_add_u32 s98, s98, 0x8000
	s_addc_u32 s99, s99, 0
	global_load_dword v250, v249, s[98:99]
	s_add_u32 s98, s98, 0x8000
	s_addc_u32 s99, s99, 0
	global_load_dword v250, v249, s[98:99]
	s_add_u32 s98, s98, 0x8000
	s_addc_u32 s99, s99, 0
	global_load_dword v250, v249, s[98:99]
	s_add_u32 s98, s98, 0x8000
	s_addc_u32 s99, s99, 0
	global_load_dword v250, v249, s[98:99]
	s_add_u32 s98, s98, 0x8000
	s_addc_u32 s99, s99, 0
	global_load_dword v250, v249, s[98:99]
	s_add_u32 s98, s98, 0x8000
	s_addc_u32 s99, s99, 0
	global_load_dword v250, v249, s[98:99]
	s_add_u32 s98, s98, 0x8000
	s_addc_u32 s99, s99, 0
	global_load_dword v250, v249, s[98:99]
.Lpf_done:
	s_addc_u32 s5, s1, 0
	v_readfirstlane_b32 s85, v153
	v_cmp_gt_u32_e32 vcc, 16, v153
	s_waitcnt lgkmcnt(0)
	v_writelane_b32 v251, s2, 0
	s_and_saveexec_b64 s[2:3], vcc
	v_lshl_add_u32 v1, v153, 2, 0
	v_add_u32_e32 v1, 0x23fc0, v1
	v_mov_b32_e32 v2, 0
	ds_write_b32 v1, v2
	s_or_b64 exec, exec, s[2:3]
	s_waitcnt lgkmcnt(0)
	s_barrier
	s_getreg_b32 s2, hwreg(HW_REG_XCC_ID, 0, 4)
	s_and_b32 s84, s2, 15
	v_cmp_eq_u32_e64 s[6:7], 0, v153
	s_mov_b64 s[2:3], exec
	s_nop 0
	v_writelane_b32 v251, s6, 1
	s_nop 1
	v_writelane_b32 v251, s7, 2
	s_and_b64 s[6:7], s[2:3], s[6:7]
	s_mov_b64 exec, s[6:7]
	s_cbranch_execz .LBB0_5
	s_mov_b64 s[6:7], exec
	v_mbcnt_lo_u32_b32 v1, s6, 0
	v_mbcnt_hi_u32_b32 v1, s7, v1
	v_cmp_eq_u32_e32 vcc, 0, v1
	s_and_b64 s[8:9], exec, vcc
	s_mov_b64 exec, s[8:9]
	s_cbranch_execz .LBB0_5
	s_lshl_b32 s8, s84, 8
	s_bcnt1_i32_b64 s6, s[6:7]
	v_mov_b32_e32 v1, s8
	v_mov_b32_e32 v2, s6
	global_atomic_add v1, v2, s[96:97] offset:1024

	.amdhsa_kernel _Z10hybrid_fwd3Prmii
		.amdhsa_group_segment_fixed_size 0
		.amdhsa_private_segment_fixed_size 0
		.amdhsa_kernarg_size 544
		.amdhsa_user_sgpr_count 2
		.amdhsa_user_sgpr_dispatch_ptr 0
		.amdhsa_user_sgpr_queue_ptr 0
		.amdhsa_user_sgpr_kernarg_segment_ptr 1
		.amdhsa_user_sgpr_dispatch_id 0
		.amdhsa_user_sgpr_kernarg_preload_length 0
		.amdhsa_user_sgpr_kernarg_preload_offset 0
		.amdhsa_user_sgpr_private_segment_size 0
		.amdhsa_uses_dynamic_stack 0
		.amdhsa_enable_private_segment 0
		.amdhsa_system_sgpr_workgroup_id_x 1
		.amdhsa_system_sgpr_workgroup_id_y 0
		.amdhsa_system_sgpr_workgroup_id_z 0
		.amdhsa_system_sgpr_workgroup_info 0
		.amdhsa_system_vgpr_workitem_id 2
		.amdhsa_next_free_vgpr 252
		.amdhsa_next_free_sgpr 100
		.amdhsa_accum_offset 252
		.amdhsa_reserve_vcc 1
		.amdhsa_float_round_mode_32 0
		.amdhsa_float_round_mode_16_64 0
		.amdhsa_float_denorm_mode_32 3
		.amdhsa_float_denorm_mode_16_64 3
		.amdhsa_dx10_clamp 1
		.amdhsa_ieee_mode 1
		.amdhsa_fp16_overflow 0
		.amdhsa_tg_split 0
		.amdhsa_exception_fp_ieee_invalid_op 0
		.amdhsa_exception_fp_denorm_src 0
		.amdhsa_exception_fp_ieee_div_zero 0
		.amdhsa_exception_fp_ieee_overflow 0
		.amdhsa_exception_fp_ieee_underflow 0
		.amdhsa_exception_fp_ieee_inexact 0
		.amdhsa_exception_int_div_zero 0
	.end_amdhsa_kernel

amdhsa.kernels:
  - .agpr_count:     0
    .args:
      - .offset:         0
        .size:           280
        .value_kind:     by_value
      - .offset:         280
        .size:           4
        .value_kind:     by_value
      - .offset:         284
        .size:           4
        .value_kind:     by_value
      - .offset:         288
        .size:           4
        .value_kind:     hidden_block_count_x
      - .offset:         292
        .size:           4
        .value_kind:     hidden_block_count_y
      - .offset:         296
        .size:           4
        .value_kind:     hidden_block_count_z
      - .offset:         300
        .size:           2
        .value_kind:     hidden_group_size_x
      - .offset:         302
        .size:           2
        .value_kind:     hidden_group_size_y
      - .offset:         304
        .size:           2
        .value_kind:     hidden_group_size_z
      - .offset:         306
        .size:           2
        .value_kind:     hidden_remainder_x
      - .offset:         308
        .size:           2
        .value_kind:     hidden_remainder_y
      - .offset:         310
        .size:           2
        .value_kind:     hidden_remainder_z
      - .offset:         328
        .size:           8
        .value_kind:     hidden_global_offset_x
      - .offset:         336
        .size:           8
        .value_kind:     hidden_global_offset_y
      - .offset:         344
        .size:           8
        .value_kind:     hidden_global_offset_z
      - .offset:         352
        .size:           2
        .value_kind:     hidden_grid_dims
      - .offset:         376
        .size:           8
        .value_kind:     hidden_multigrid_sync_arg
      - .offset:         408
        .size:           4
        .value_kind:     hidden_dynamic_lds_size
    .group_segment_fixed_size: 0
    .kernarg_segment_align: 8
    .kernarg_segment_size: 544
    .language:       OpenCL C
    .language_version:
      - 2
      - 0
    .max_flat_workgroup_size: 512
    .name:           _Z10hybrid_fwd3Prmii
    .private_segment_fixed_size: 0
    .sgpr_count:     106
    .sgpr_spill_count: 65
    .symbol:         _Z10hybrid_fwd3Prmii.kd
    .uniform_work_group_size: 1
    .uses_dynamic_stack: false
    .vgpr_count:     252
    .vgpr_spill_count: 0
    .wavefront_size: 64
